# slot conversion paced with s_sleep 32 per item to leave HBM bandwidth to the GEMM tail
# baseline (speedup 1.0000x reference)
.LBB0_10:
	s_cmp_eq_u32 s100, 0
	s_cbranch_scc1 .Lconv_nopace
	s_sleep 32
